# attention: last PV MFMA group interleaved with its row-sum adds (no back-to-back MFMAs left in exp block)
# baseline (speedup 1.0000x reference)
; #define MFMA(a, b, c) __builtin_amdgcn_mfma_f32_16x16x32_bf16((a), (b), (c), 0, 0, 0)
; template <int MODE> ...
;     ...
;         for (int hh = 0; hh < 2; ++hh) {
;           float pv[8];
; #pragma unroll
;           for (int j = 0; j < 4; ++j) {
;             pv[j] = __builtin_amdgcn_exp2f(S[kh][tt][hh][0][j]);
;             pv[4 + j] = __builtin_amdgcn_exp2f(S[kh][tt][hh][1][j]);
;           }
;           lsum[tt][hh] += ((pv[0] + pv[1]) + (pv[2] + pv[3])) + ((pv[4] + pv[5]) + (pv[6] + pv[7]));
;           const uint4 pk = make_uint4(pack2(pv[0], pv[1]), pack2(pv[2], pv[3]), pack2(pv[4], pv[5]), pack2(pv[6], pv[7]));
;           pf[hh] = __builtin_bit_cast(bf16x8, pk);
;         }
; #pragma unroll
;         for (int dt = 0; dt < 4; ++dt) {
;           const bf16x8 vf = *(const bf16x8*)&Vs[(dt * 16 + r) * 64 + (((kh * 4 + g) ^ (r & 7)) * 8)];
;           O[tt][0][dt] = MFMA(vf, pf[0], O[tt][0][dt]);
;           O[tt][1][dt] = MFMA(vf, pf[1], O[tt][1][dt]);
;         }
.Lattn1_nw:
	v_exp_f32_e32 v135, v140
	v_exp_f32_e32 v131, v144
	v_exp_f32_e32 v139, v141
	v_exp_f32_e32 v137, v145
	v_exp_f32_e32 v124, v164
	v_exp_f32_e32 v128, v165
	v_exp_f32_e32 v130, v166
	v_exp_f32_e32 v136, v167
	v_pk_add_f32 v[248:249], v[132:133], v[126:127]
	v_pk_add_f32 v[250:251], v[138:139], v[134:135]
	v_pk_add_f32 v[248:249], v[250:251], v[248:249]
	v_pk_add_f32 v[250:251], v[128:129], v[124:125]
	v_pk_add_f32 v[252:253], v[136:137], v[130:131]
	v_pk_add_f32 v[250:251], v[252:253], v[250:251]
	v_pk_add_f32 v[248:249], v[250:251], v[248:249]
	v_pk_add_f32 v[188:189], v[248:249], v[188:189]
	v_cvt_pk_bf16_f32 v240, v126, v132
	v_cvt_pk_bf16_f32 v241, v134, v138
	v_cvt_pk_bf16_f32 v242, v124, v128
	v_cvt_pk_bf16_f32 v243, v130, v136
	v_cvt_pk_bf16_f32 v244, v127, v133
	v_cvt_pk_bf16_f32 v245, v135, v139
	v_cvt_pk_bf16_f32 v246, v125, v129
	v_cvt_pk_bf16_f32 v247, v131, v137
	s_waitcnt lgkmcnt(0)
	v_mfma_f32_16x16x32_bf16 v[52:55], v[208:211], v[240:243], v[52:55]
	v_exp_f32_e32 v148, v148
	v_mfma_f32_16x16x32_bf16 v[60:63], v[212:215], v[240:243], v[60:63]
	v_exp_f32_e32 v146, v152
	v_mfma_f32_16x16x32_bf16 v[56:59], v[216:219], v[240:243], v[56:59]
	v_exp_f32_e32 v152, v153
	v_mfma_f32_16x16x32_bf16 v[64:67], v[220:223], v[240:243], v[64:67]
	v_exp_f32_e32 v145, v163
	v_mfma_f32_16x16x32_bf16 v[44:47], v[208:211], v[244:247], v[44:47]
	v_exp_f32_e32 v141, v162
	v_mfma_f32_16x16x32_bf16 v[40:43], v[212:215], v[244:247], v[40:43]
	v_exp_f32_e32 v147, v160
	v_mfma_f32_16x16x32_bf16 v[36:39], v[216:219], v[244:247], v[36:39]
	v_exp_f32_e32 v153, v161
	v_mfma_f32_16x16x32_bf16 v[48:51], v[220:223], v[244:247], v[48:51]
	v_exp_f32_e32 v142, v150
	v_exp_f32_e32 v140, v154
	v_exp_f32_e32 v150, v151
	v_exp_f32_e32 v144, v155
	v_exp_f32_e32 v154, v149
	v_exp_f32_e32 v143, v158
	v_exp_f32_e32 v151, v159
	v_exp_f32_e32 v149, v156
	v_exp_f32_e32 v155, v157
	v_cvt_pk_bf16_f32 v240, v142, v150
	v_cvt_pk_bf16_f32 v241, v148, v154
	v_cvt_pk_bf16_f32 v242, v140, v144
	v_cvt_pk_bf16_f32 v243, v146, v152
	v_cvt_pk_bf16_f32 v244, v143, v151
	v_cvt_pk_bf16_f32 v245, v149, v155
	v_cvt_pk_bf16_f32 v246, v141, v145
	v_cvt_pk_bf16_f32 v247, v147, v153
	v_mfma_f32_16x16x32_bf16 v[32:35], v[208:211], v[240:243], v[32:35]
	v_pk_add_f32 v[248:249], v[150:151], v[142:143]
	v_mfma_f32_16x16x32_bf16 v[28:31], v[212:215], v[240:243], v[28:31]
	v_pk_add_f32 v[250:251], v[154:155], v[148:149]
	v_mfma_f32_16x16x32_bf16 v[24:27], v[216:219], v[240:243], v[24:27]
	v_pk_add_f32 v[248:249], v[250:251], v[248:249]
	v_mfma_f32_16x16x32_bf16 v[20:23], v[220:223], v[240:243], v[20:23]
	v_pk_add_f32 v[250:251], v[144:145], v[140:141]
	v_mfma_f32_16x16x32_bf16 v[16:19], v[208:211], v[244:247], v[16:19]
	v_pk_add_f32 v[252:253], v[152:153], v[146:147]
	v_mfma_f32_16x16x32_bf16 v[12:15], v[212:215], v[244:247], v[12:15]
	v_pk_add_f32 v[250:251], v[252:253], v[250:251]
	v_mfma_f32_16x16x32_bf16 v[8:11], v[216:219], v[244:247], v[8:11]
	v_pk_add_f32 v[248:249], v[250:251], v[248:249]
	v_mfma_f32_16x16x32_bf16 v[4:7], v[220:223], v[244:247], v[4:7]
	v_pk_add_f32 v[186:187], v[248:249], v[186:187]
	s_andn2_b64 vcc, exec, s[56:57]
	s_cbranch_vccz .Lattn1_adv

; #define MFMA(a, b, c) __builtin_amdgcn_mfma_f32_16x16x32_bf16((a), (b), (c), 0, 0, 0)
; template <int MODE> ...
;     ...
;         for (int hh = 0; hh < 2; ++hh) {
;           float pv[8];
; #pragma unroll
;           for (int j = 0; j < 4; ++j) {
;             pv[j] = __builtin_amdgcn_exp2f(S[kh][tt][hh][0][j]);
;             pv[4 + j] = __builtin_amdgcn_exp2f(S[kh][tt][hh][1][j]);
;           }
;           lsum[tt][hh] += ((pv[0] + pv[1]) + (pv[2] + pv[3])) + ((pv[4] + pv[5]) + (pv[6] + pv[7]));
;           const uint4 pk = make_uint4(pack2(pv[0], pv[1]), pack2(pv[2], pv[3]), pack2(pv[4], pv[5]), pack2(pv[6], pv[7]));
;           pf[hh] = __builtin_bit_cast(bf16x8, pk);
;         }
; #pragma unroll
;         for (int dt = 0; dt < 4; ++dt) {
;           const bf16x8 vf = *(const bf16x8*)&Vs[(dt * 16 + r) * 64 + (((kh * 4 + g) ^ (r & 7)) * 8)];
;           O[tt][0][dt] = MFMA(vf, pf[0], O[tt][0][dt]);
;           O[tt][1][dt] = MFMA(vf, pf[1], O[tt][1][dt]);
;         }
.Lattn2_nw:
	v_exp_f32_e32 v117, v122
	v_exp_f32_e32 v113, v126
	v_exp_f32_e32 v121, v123
	v_exp_f32_e32 v119, v127
	v_exp_f32_e32 v106, v146
	v_exp_f32_e32 v110, v147
	v_exp_f32_e32 v112, v148
	v_exp_f32_e32 v118, v149
	v_pk_add_f32 v[248:249], v[114:115], v[108:109]
	v_pk_add_f32 v[250:251], v[120:121], v[116:117]
	v_pk_add_f32 v[248:249], v[250:251], v[248:249]
	v_pk_add_f32 v[250:251], v[110:111], v[106:107]
	v_pk_add_f32 v[252:253], v[118:119], v[112:113]
	v_pk_add_f32 v[250:251], v[252:253], v[250:251]
	v_pk_add_f32 v[248:249], v[250:251], v[248:249]
	v_pk_add_f32 v[170:171], v[248:249], v[170:171]
	v_cvt_pk_bf16_f32 v240, v108, v114
	v_cvt_pk_bf16_f32 v241, v116, v120
	v_cvt_pk_bf16_f32 v242, v106, v110
	v_cvt_pk_bf16_f32 v243, v112, v118
	v_cvt_pk_bf16_f32 v244, v109, v115
	v_cvt_pk_bf16_f32 v245, v117, v121
	v_cvt_pk_bf16_f32 v246, v107, v111
	v_cvt_pk_bf16_f32 v247, v113, v119
	s_waitcnt lgkmcnt(0)
	v_mfma_f32_16x16x32_bf16 v[70:73], v[200:203], v[240:243], v[70:73]
	v_exp_f32_e32 v130, v130
	v_mfma_f32_16x16x32_bf16 v[78:81], v[204:207], v[240:243], v[78:81]
	v_exp_f32_e32 v128, v134
	v_mfma_f32_16x16x32_bf16 v[62:65], v[208:211], v[240:243], v[62:65]
	v_exp_f32_e32 v134, v135
	v_mfma_f32_16x16x32_bf16 v[74:77], v[212:215], v[240:243], v[74:77]
	v_exp_f32_e32 v127, v145
	v_mfma_f32_16x16x32_bf16 v[86:89], v[200:203], v[244:247], v[86:89]
	v_exp_f32_e32 v123, v144
	v_mfma_f32_16x16x32_bf16 v[66:69], v[204:207], v[244:247], v[66:69]
	v_exp_f32_e32 v129, v142
	v_mfma_f32_16x16x32_bf16 v[58:61], v[208:211], v[244:247], v[58:61]
	v_exp_f32_e32 v135, v143
	v_mfma_f32_16x16x32_bf16 v[82:85], v[212:215], v[244:247], v[82:85]
	v_exp_f32_e32 v124, v132
	v_exp_f32_e32 v122, v136
	v_exp_f32_e32 v132, v133
	v_exp_f32_e32 v126, v137
	v_exp_f32_e32 v136, v131
	v_exp_f32_e32 v125, v140
	v_exp_f32_e32 v133, v141
	v_exp_f32_e32 v131, v138
	v_exp_f32_e32 v137, v139
	v_cvt_pk_bf16_f32 v240, v124, v132
	v_cvt_pk_bf16_f32 v241, v130, v136
	v_cvt_pk_bf16_f32 v242, v122, v126
	v_cvt_pk_bf16_f32 v243, v128, v134
	v_cvt_pk_bf16_f32 v244, v125, v133
	v_cvt_pk_bf16_f32 v245, v131, v137
	v_cvt_pk_bf16_f32 v246, v123, v127
	v_cvt_pk_bf16_f32 v247, v129, v135
	v_mfma_f32_16x16x32_bf16 v[42:45], v[200:203], v[240:243], v[42:45]
	v_pk_add_f32 v[248:249], v[132:133], v[124:125]
	v_mfma_f32_16x16x32_bf16 v[34:37], v[204:207], v[240:243], v[34:37]
	v_pk_add_f32 v[250:251], v[136:137], v[130:131]
	v_mfma_f32_16x16x32_bf16 v[10:13], v[208:211], v[240:243], v[10:13]
	v_pk_add_f32 v[248:249], v[250:251], v[248:249]
	v_mfma_f32_16x16x32_bf16 v[6:9], v[212:215], v[240:243], v[6:9]
	v_pk_add_f32 v[250:251], v[126:127], v[122:123]
	v_mfma_f32_16x16x32_bf16 v[46:49], v[200:203], v[244:247], v[46:49]
	v_pk_add_f32 v[252:253], v[134:135], v[128:129]
	v_mfma_f32_16x16x32_bf16 v[38:41], v[204:207], v[244:247], v[38:41]
	v_pk_add_f32 v[250:251], v[252:253], v[250:251]
	v_mfma_f32_16x16x32_bf16 v[14:17], v[208:211], v[244:247], v[14:17]
	v_pk_add_f32 v[248:249], v[250:251], v[248:249]
	v_mfma_f32_16x16x32_bf16 v[2:5], v[212:215], v[244:247], v[2:5]
	v_pk_add_f32 v[156:157], v[248:249], v[156:157]
	s_andn2_b64 vcc, exec, s[48:49]
	s_cbranch_vccz .Lattn2_adv
